# NSA selected branch: the four K-row addresses of a gathered block collapse to one base plus immediate offsets
# speedup vs baseline: 1.0729x; 1.0071x over previous
; #define LAS __attribute__((address_space(3)))
; __device__ __forceinline__ void sel_load(SelBuf& B, const unsigned char* Kb, const unsigned char* Vb, int jb, int cc, int q4) {
; #pragma unroll
;     for (int ht = 0; ht < 4; ++ht) { const int keyrow = jb * 64 + 32 * (ht >> 1) + 8 * (cc >> 2) + (cc & 3) + 4 * (ht & 1);
;         B.k[ht] = *(const l64x2*)(Kb + (size_t)keyrow * 64 + q4 * 16); }
; #pragma unroll
;     for (int d = 0; d < 4; ++d) B.v[d] = *(const l64x2*)(Vb + ((size_t)jb * 64 + 16 * d + cc) * 64 + q4 * 16);
; }
; __device__ __forceinline__ void sel_load_any(SelBuf& B, const unsigned char* Kb, const unsigned char* Vb, const LAS unsigned char* fl, int jb, int cur, int cc, int q4) {
;     const int slot = (jb == 0) ? 0 : ((jb == cur - 1) ? 1 : ((jb == cur) ? 2 : -1));
;     if (slot < 0) { sel_load(B, Kb, Vb, jb, cc, q4); return; }
.LBB0_633:
	s_or_saveexec_b64 s[2:3], s[2:3]
	v_lshl_add_u64 v[206:207], s[6:7], 0, v[194:195]
	v_lshl_add_u64 v[138:139], s[4:5], 0, v[194:195]
	s_xor_b64 exec, exec, s[2:3]
	s_cbranch_execz .LBB0_635
	s_waitcnt lgkmcnt(0)
	v_ashrrev_i32_e32 v199, 31, v198
	v_lshlrev_b64 v[18:19], 12, v[198:199]
	v_lshl_add_u64 v[18:19], v[138:139], 0, v[18:19]
	v_lshl_add_u64 v[22:23], v[18:19], 0, v[196:197]
	v_lshl_or_b32 v14, v198, 6, v193
	v_ashrrev_i32_e32 v15, 31, v14
	v_lshlrev_b64 v[14:15], 6, v[14:15]
	v_lshl_add_u64 v[14:15], v[206:207], 0, v[14:15]
	global_load_dwordx4 v[2:5], v[14:15], off
	global_load_dwordx4 v[6:9], v[14:15], off offset:256
	global_load_dwordx4 v[10:13], v[14:15], off offset:2048
	s_nop 0
	global_load_dwordx4 v[14:17], v[14:15], off offset:2304
	s_nop 0
	global_load_dwordx4 v[18:21], v[22:23], off
	global_load_dwordx4 v[26:29], v[22:23], off offset:1024
	global_load_dwordx4 v[30:33], v[22:23], off offset:2048
	s_nop 0
	global_load_dwordx4 v[22:25], v[22:23], off offset:3072

; #define LAS __attribute__((address_space(3)))
; __device__ __forceinline__ void sel_load(SelBuf& B, const unsigned char* Kb, const unsigned char* Vb, int jb, int cc, int q4) {
; #pragma unroll
;     for (int ht = 0; ht < 4; ++ht) { const int keyrow = jb * 64 + 32 * (ht >> 1) + 8 * (cc >> 2) + (cc & 3) + 4 * (ht & 1);
;         B.k[ht] = *(const l64x2*)(Kb + (size_t)keyrow * 64 + q4 * 16); }
; #pragma unroll
;     for (int d = 0; d < 4; ++d) B.v[d] = *(const l64x2*)(Vb + ((size_t)jb * 64 + 16 * d + cc) * 64 + q4 * 16);
; }
; __device__ __forceinline__ void sel_load_any(SelBuf& B, const unsigned char* Kb, const unsigned char* Vb, const LAS unsigned char* fl, int jb, int cur, int cc, int q4) {
;     const int slot = (jb == 0) ? 0 : ((jb == cur - 1) ? 1 : ((jb == cur) ? 2 : -1));
;     if (slot < 0) { sel_load(B, Kb, Vb, jb, cc, q4); return; }
.LBB0_637:
	s_andn2_saveexec_b64 s[2:3], s[2:3]
	s_cbranch_execz .LBB0_639
	s_waitcnt lgkmcnt(0)
	v_lshl_or_b32 v58, v202, 6, v193
	v_ashrrev_i32_e32 v59, 31, v58
	v_lshlrev_b64 v[58:59], 6, v[58:59]
	v_lshl_add_u64 v[58:59], v[206:207], 0, v[58:59]
	global_load_dwordx4 v[34:37], v[58:59], off
	global_load_dwordx4 v[42:45], v[58:59], off offset:256
	global_load_dwordx4 v[50:53], v[58:59], off offset:2048
	s_nop 0
	global_load_dwordx4 v[58:61], v[58:59], off offset:2304
	v_ashrrev_i32_e32 v203, 31, v202
	v_lshlrev_b64 v[38:39], 12, v[202:203]
	v_lshl_add_u64 v[38:39], v[138:139], 0, v[38:39]
	v_lshl_add_u64 v[38:39], v[38:39], 0, v[196:197]
	global_load_dwordx4 v[66:69], v[38:39], off
	global_load_dwordx4 v[78:81], v[38:39], off offset:1024
	global_load_dwordx4 v[90:93], v[38:39], off offset:2048
	global_load_dwordx4 v[86:89], v[38:39], off offset:3072

; #define LAS __attribute__((address_space(3)))
; __device__ __forceinline__ void sel_load(SelBuf& B, const unsigned char* Kb, const unsigned char* Vb, int jb, int cc, int q4) {
; #pragma unroll
;     for (int ht = 0; ht < 4; ++ht) { const int keyrow = jb * 64 + 32 * (ht >> 1) + 8 * (cc >> 2) + (cc & 3) + 4 * (ht & 1);
;         B.k[ht] = *(const l64x2*)(Kb + (size_t)keyrow * 64 + q4 * 16); }
; #pragma unroll
;     for (int d = 0; d < 4; ++d) B.v[d] = *(const l64x2*)(Vb + ((size_t)jb * 64 + 16 * d + cc) * 64 + q4 * 16);
; }
; __device__ __forceinline__ void sel_load_any(SelBuf& B, const unsigned char* Kb, const unsigned char* Vb, const LAS unsigned char* fl, int jb, int cur, int cc, int q4) {
;     const int slot = (jb == 0) ? 0 : ((jb == cur - 1) ? 1 : ((jb == cur) ? 2 : -1));
;     if (slot < 0) { sel_load(B, Kb, Vb, jb, cc, q4); return; }
.LBB0_641:
	s_andn2_saveexec_b64 s[2:3], s[2:3]
	s_cbranch_execz .LBB0_643
	s_waitcnt lgkmcnt(0)
	v_ashrrev_i32_e32 v201, 31, v200
	v_lshlrev_b64 v[70:71], 12, v[200:201]
	v_lshl_add_u64 v[70:71], v[138:139], 0, v[70:71]
	v_lshl_add_u64 v[74:75], v[70:71], 0, v[196:197]
	v_lshl_or_b32 v62, v200, 6, v193
	v_ashrrev_i32_e32 v63, 31, v62
	v_lshlrev_b64 v[62:63], 6, v[62:63]
	v_lshl_add_u64 v[62:63], v[206:207], 0, v[62:63]
	global_load_dwordx4 v[38:41], v[62:63], off
	global_load_dwordx4 v[46:49], v[62:63], off offset:256
	global_load_dwordx4 v[54:57], v[62:63], off offset:2048
	s_nop 0
	global_load_dwordx4 v[62:65], v[62:63], off offset:2304
	s_nop 0
	global_load_dwordx4 v[70:73], v[74:75], off
	global_load_dwordx4 v[82:85], v[74:75], off offset:1024
	global_load_dwordx4 v[94:97], v[74:75], off offset:2048
	s_nop 0
	global_load_dwordx4 v[74:77], v[74:75], off offset:3072

; #define LAS __attribute__((address_space(3)))
; __device__ __forceinline__ void sel_load(SelBuf& B, const unsigned char* Kb, const unsigned char* Vb, int jb, int cc, int q4) {
; #pragma unroll
;     for (int ht = 0; ht < 4; ++ht) { const int keyrow = jb * 64 + 32 * (ht >> 1) + 8 * (cc >> 2) + (cc & 3) + 4 * (ht & 1);
;         B.k[ht] = *(const l64x2*)(Kb + (size_t)keyrow * 64 + q4 * 16); }
; #pragma unroll
;     for (int d = 0; d < 4; ++d) B.v[d] = *(const l64x2*)(Vb + ((size_t)jb * 64 + 16 * d + cc) * 64 + q4 * 16);
; }
; __device__ __forceinline__ void sel_load_any(SelBuf& B, const unsigned char* Kb, const unsigned char* Vb, const LAS unsigned char* fl, int jb, int cur, int cc, int q4) {
;     const int slot = (jb == 0) ? 0 : ((jb == cur - 1) ? 1 : ((jb == cur) ? 2 : -1));
;     if (slot < 0) { sel_load(B, Kb, Vb, jb, cc, q4); return; }
.LBB0_719:
	s_andn2_saveexec_b64 s[2:3], s[2:3]
	s_cbranch_execz .LBB0_721
	s_waitcnt lgkmcnt(5)
	v_ashrrev_i32_e32 v199, 31, v198
	s_waitcnt lgkmcnt(3)
	v_lshlrev_b64 v[18:19], 12, v[198:199]
	s_waitcnt lgkmcnt(0)
	v_lshl_add_u64 v[22:23], v[212:213], 0, v[18:19]
	v_lshl_or_b32 v14, v198, 6, v193
	v_ashrrev_i32_e32 v15, 31, v14
	v_lshlrev_b64 v[14:15], 6, v[14:15]
	v_lshl_add_u64 v[14:15], v[206:207], 0, v[14:15]
	global_load_dwordx4 v[2:5], v[14:15], off
	global_load_dwordx4 v[6:9], v[14:15], off offset:256
	global_load_dwordx4 v[10:13], v[14:15], off offset:2048
	s_nop 0
	global_load_dwordx4 v[14:17], v[14:15], off offset:2304
	s_nop 0
	global_load_dwordx4 v[18:21], v[22:23], off
	global_load_dwordx4 v[26:29], v[22:23], off offset:1024
	global_load_dwordx4 v[30:33], v[22:23], off offset:2048
	s_nop 0
	global_load_dwordx4 v[22:25], v[22:23], off offset:3072

; #define LAS __attribute__((address_space(3)))
; __device__ __forceinline__ void sel_load(SelBuf& B, const unsigned char* Kb, const unsigned char* Vb, int jb, int cc, int q4) {
; #pragma unroll
;     for (int ht = 0; ht < 4; ++ht) { const int keyrow = jb * 64 + 32 * (ht >> 1) + 8 * (cc >> 2) + (cc & 3) + 4 * (ht & 1);
;         B.k[ht] = *(const l64x2*)(Kb + (size_t)keyrow * 64 + q4 * 16); }
; #pragma unroll
;     for (int d = 0; d < 4; ++d) B.v[d] = *(const l64x2*)(Vb + ((size_t)jb * 64 + 16 * d + cc) * 64 + q4 * 16);
; }
; __device__ __forceinline__ void sel_load_any(SelBuf& B, const unsigned char* Kb, const unsigned char* Vb, const LAS unsigned char* fl, int jb, int cur, int cc, int q4) {
;     const int slot = (jb == 0) ? 0 : ((jb == cur - 1) ? 1 : ((jb == cur) ? 2 : -1));
;     if (slot < 0) { sel_load(B, Kb, Vb, jb, cc, q4); return; }
.LBB0_723:
	s_andn2_saveexec_b64 s[2:3], s[2:3]
	s_cbranch_execz .LBB0_725
	s_waitcnt lgkmcnt(5)
	v_ashrrev_i32_e32 v203, 31, v202
	s_waitcnt lgkmcnt(3)
	v_lshlrev_b64 v[66:67], 12, v[202:203]
	s_waitcnt lgkmcnt(0)
	v_lshl_add_u64 v[86:87], v[212:213], 0, v[66:67]
	v_lshl_or_b32 v58, v202, 6, v193
	v_ashrrev_i32_e32 v59, 31, v58
	v_lshlrev_b64 v[58:59], 6, v[58:59]
	v_lshl_add_u64 v[58:59], v[206:207], 0, v[58:59]
	global_load_dwordx4 v[34:37], v[58:59], off
	global_load_dwordx4 v[42:45], v[58:59], off offset:256
	global_load_dwordx4 v[50:53], v[58:59], off offset:2048
	s_nop 0
	global_load_dwordx4 v[58:61], v[58:59], off offset:2304
	s_nop 0
	global_load_dwordx4 v[66:69], v[86:87], off
	global_load_dwordx4 v[78:81], v[86:87], off offset:1024
	global_load_dwordx4 v[90:93], v[86:87], off offset:2048
	s_nop 0
	global_load_dwordx4 v[86:89], v[86:87], off offset:3072

; #define LAS __attribute__((address_space(3)))
; __device__ __forceinline__ void sel_load(SelBuf& B, const unsigned char* Kb, const unsigned char* Vb, int jb, int cc, int q4) {
; #pragma unroll
;     for (int ht = 0; ht < 4; ++ht) { const int keyrow = jb * 64 + 32 * (ht >> 1) + 8 * (cc >> 2) + (cc & 3) + 4 * (ht & 1);
;         B.k[ht] = *(const l64x2*)(Kb + (size_t)keyrow * 64 + q4 * 16); }
; #pragma unroll
;     for (int d = 0; d < 4; ++d) B.v[d] = *(const l64x2*)(Vb + ((size_t)jb * 64 + 16 * d + cc) * 64 + q4 * 16);
; }
; __device__ __forceinline__ void sel_load_any(SelBuf& B, const unsigned char* Kb, const unsigned char* Vb, const LAS unsigned char* fl, int jb, int cur, int cc, int q4) {
;     const int slot = (jb == 0) ? 0 : ((jb == cur - 1) ? 1 : ((jb == cur) ? 2 : -1));
;     if (slot < 0) { sel_load(B, Kb, Vb, jb, cc, q4); return; }
.LBB0_800:
	s_andn2_saveexec_b64 s[2:3], s[2:3]
	s_cbranch_execz .LBB0_802
	s_waitcnt lgkmcnt(5)
	v_ashrrev_i32_e32 v201, 31, v200
	s_waitcnt lgkmcnt(3)
	v_lshlrev_b64 v[70:71], 12, v[200:201]
	s_waitcnt lgkmcnt(0)
	v_lshl_add_u64 v[74:75], v[212:213], 0, v[70:71]
	v_lshl_or_b32 v62, v200, 6, v193
	v_ashrrev_i32_e32 v63, 31, v62
	v_lshlrev_b64 v[62:63], 6, v[62:63]
	v_lshl_add_u64 v[62:63], v[206:207], 0, v[62:63]
	global_load_dwordx4 v[38:41], v[62:63], off
	global_load_dwordx4 v[46:49], v[62:63], off offset:256
	global_load_dwordx4 v[54:57], v[62:63], off offset:2048
	s_nop 0
	global_load_dwordx4 v[62:65], v[62:63], off offset:2304
	s_nop 0
	global_load_dwordx4 v[70:73], v[74:75], off
	global_load_dwordx4 v[82:85], v[74:75], off offset:1024
	global_load_dwordx4 v[94:97], v[74:75], off offset:2048
	s_nop 0
	global_load_dwordx4 v[74:77], v[74:75], off offset:3072

; #define LAS __attribute__((address_space(3)))
; __device__ __forceinline__ void sel_load(SelBuf& B, const unsigned char* Kb, const unsigned char* Vb, int jb, int cc, int q4) {
; #pragma unroll
;     for (int ht = 0; ht < 4; ++ht) { const int keyrow = jb * 64 + 32 * (ht >> 1) + 8 * (cc >> 2) + (cc & 3) + 4 * (ht & 1);
;         B.k[ht] = *(const l64x2*)(Kb + (size_t)keyrow * 64 + q4 * 16); }
; #pragma unroll
;     for (int d = 0; d < 4; ++d) B.v[d] = *(const l64x2*)(Vb + ((size_t)jb * 64 + 16 * d + cc) * 64 + q4 * 16);
; }
; __device__ __forceinline__ void sel_load_any(SelBuf& B, const unsigned char* Kb, const unsigned char* Vb, const LAS unsigned char* fl, int jb, int cur, int cc, int q4) {
;     const int slot = (jb == 0) ? 0 : ((jb == cur - 1) ? 1 : ((jb == cur) ? 2 : -1));
;     if (slot < 0) { sel_load(B, Kb, Vb, jb, cc, q4); return; }
.LBB0_804:
	s_andn2_saveexec_b64 s[2:3], s[2:3]
	s_cbranch_execz .LBB0_806
	s_waitcnt lgkmcnt(5)
	v_ashrrev_i32_e32 v205, 31, v204
	s_waitcnt lgkmcnt(3)
	v_lshlrev_b64 v[122:123], 12, v[204:205]
	s_waitcnt lgkmcnt(0)
	v_lshl_add_u64 v[130:131], v[212:213], 0, v[122:123]
	v_lshl_or_b32 v118, v204, 6, v193
	v_ashrrev_i32_e32 v119, 31, v118
	v_lshlrev_b64 v[118:119], 6, v[118:119]
	v_lshl_add_u64 v[118:119], v[206:207], 0, v[118:119]
	global_load_dwordx4 v[102:105], v[118:119], off
	global_load_dwordx4 v[106:109], v[118:119], off offset:256
	global_load_dwordx4 v[114:117], v[118:119], off offset:2048
	s_nop 0
	global_load_dwordx4 v[118:121], v[118:119], off offset:2304
	s_nop 0
	global_load_dwordx4 v[122:125], v[130:131], off
	global_load_dwordx4 v[126:129], v[130:131], off offset:1024
	global_load_dwordx4 v[134:137], v[130:131], off offset:2048
	s_nop 0
	global_load_dwordx4 v[130:133], v[130:131], off offset:3072

; #define LAS __attribute__((address_space(3)))
; __device__ __forceinline__ void sel_load(SelBuf& B, const unsigned char* Kb, const unsigned char* Vb, int jb, int cc, int q4) {
; #pragma unroll
;     for (int ht = 0; ht < 4; ++ht) { const int keyrow = jb * 64 + 32 * (ht >> 1) + 8 * (cc >> 2) + (cc & 3) + 4 * (ht & 1);
;         B.k[ht] = *(const l64x2*)(Kb + (size_t)keyrow * 64 + q4 * 16); }
; #pragma unroll
;     for (int d = 0; d < 4; ++d) B.v[d] = *(const l64x2*)(Vb + ((size_t)jb * 64 + 16 * d + cc) * 64 + q4 * 16);
; }
; __device__ __forceinline__ void sel_load_any(SelBuf& B, const unsigned char* Kb, const unsigned char* Vb, const LAS unsigned char* fl, int jb, int cur, int cc, int q4) {
;     const int slot = (jb == 0) ? 0 : ((jb == cur - 1) ? 1 : ((jb == cur) ? 2 : -1));
;     if (slot < 0) { sel_load(B, Kb, Vb, jb, cc, q4); return; }
; __device__ __forceinline__ void phase_sel(const Params& p, LAS unsigned char* lds, const bf16_t* Z, const float* G, const unsigned char* K8, const unsigned char* V8T, const float* ACC, const int* IDX, bf16_t* Mixed, int tid, int wid, int lane) {
;     ...
;         sel_load_any(b0, Kb, Vb, lds, j0, cur, cc, q4); sel_load_any(b1, Kb, Vb, lds, j1, cur, cc, q4); sel_load_any(b2, Kb, Vb, lds, j2, cur, cc, q4); sel_load_any(b3, Kb, Vb, lds, j3, cur, cc, q4);
;         for (int k = 0; k < nblk; k += 4) {
.LBB0_811:
	s_waitcnt lgkmcnt(0)
	v_ashrrev_i32_e32 v205, 31, v204
	v_lshlrev_b64 v[122:123], 12, v[204:205]
	v_lshl_add_u64 v[122:123], v[138:139], 0, v[122:123]
	v_lshl_add_u64 v[130:131], v[122:123], 0, v[196:197]
	v_lshl_or_b32 v118, v204, 6, v193
	v_ashrrev_i32_e32 v119, 31, v118
	v_lshlrev_b64 v[118:119], 6, v[118:119]
	v_lshl_add_u64 v[118:119], v[206:207], 0, v[118:119]
	global_load_dwordx4 v[102:105], v[118:119], off
	global_load_dwordx4 v[106:109], v[118:119], off offset:256
	global_load_dwordx4 v[114:117], v[118:119], off offset:2048
	s_nop 0
	global_load_dwordx4 v[118:121], v[118:119], off offset:2304
	s_nop 0
	global_load_dwordx4 v[122:125], v[130:131], off
	global_load_dwordx4 v[126:129], v[130:131], off offset:1024
	global_load_dwordx4 v[134:137], v[130:131], off offset:2048
	s_nop 0
	global_load_dwordx4 v[130:133], v[130:131], off offset:3072
	s_or_b64 exec, exec, s[2:3]
	s_cmp_eq_u64 vcc, 0
	s_cbranch_scc0 .LBB0_646
